# adds: GLA per-lane load offsets computed once per job (loop set-up is scalar only)
# baseline (speedup 1.0000x reference)
.LBB0_1315:
	s_lshl_b32 s10, s53, 2
	s_ashr_i32 s11, s53, 6
	s_and_b32 s10, s10, 28
	s_and_b32 s62, s11, 3
	s_add_i32 s31, s10, s11
	s_and_b32 s10, s53, 32
	s_bfe_i32 s63, s53, 0x10005
	s_lshl_b32 s84, s62, 8
	s_cmp_eq_u32 s10, 0
	s_cselect_b64 s[70:71], -1, 0
	s_and_b64 s[10:11], s[70:71], exec
	s_movk_i32 s11, 0xc00
	s_cselect_b32 s56, s11, 0x1000
	v_readlane_b32 s11, v253, 40
	v_readlane_b32 s57, v252, 53
	s_cselect_b32 s11, s57, s11
	v_readlane_b32 s57, v253, 39
	s_cselect_b32 s10, 1, -1
	s_cselect_b32 s74, s96, s57
	s_add_u32 s56, s34, s56
	s_addc_u32 s57, s35, 0
	s_add_u32 s56, s56, s84
	s_addc_u32 s57, s57, 0
	s_lshl_b32 s75, s62, 9
	v_readlane_b32 s62, v253, 49
	s_add_u32 s62, s62, s75
	v_readlane_b32 s64, v253, 50
	s_addc_u32 s65, s64, 0
	s_lshl_b32 s72, s53, 4
	s_and_b32 s77, s72, 0x180
	s_add_u32 s72, s62, s77
	s_addc_u32 s73, s65, 0
	s_ashr_i32 s65, s31, 2
	v_lshl_add_u64 v[46:47], v[30:31], 1, s[56:57]
	s_lshl_b32 s56, s65, 8
	s_add_i32 s56, s56, 0x10000
	s_and_b32 s31, s63, 0xff
	s_or_b32 s76, s56, s31
	s_waitcnt vmcnt(0)
	v_mov_b32_e32 v20, s76
	v_mad_i32_i24 v110, s10, v52, s10
	v_mad_i32_i24 v2, s10, v52, v20
	v_add_u32_e32 v111, s10, v110
	v_ashrrev_i32_e32 v3, 31, v2
	v_add_u32_e32 v8, s76, v110
	v_add_u32_e32 v14, s76, v111
	v_lshlrev_b64 v[2:3], 13, v[2:3]
	v_ashrrev_i32_e32 v9, 31, v8
	v_ashrrev_i32_e32 v15, 31, v14
	v_add_u32_e32 v112, s10, v111
	v_lshl_add_u64 v[42:43], v[34:35], 0, s[84:85]
	v_lshl_add_u64 v[44:45], v[36:37], 0, s[84:85]
	v_lshl_add_u64 v[4:5], v[46:47], 0, v[2:3]
	v_lshlrev_b64 v[8:9], 13, v[8:9]
	v_lshlrev_b64 v[14:15], 13, v[14:15]
	v_add_u32_e32 v113, s10, v112
	v_lshl_add_u64 v[6:7], v[44:45], 0, v[2:3]
	v_lshl_add_u64 v[2:3], v[42:43], 0, v[2:3]
	v_lshl_add_u64 v[10:11], v[46:47], 0, v[8:9]
	v_lshl_add_u64 v[12:13], v[44:45], 0, v[8:9]
	v_lshl_add_u64 v[8:9], v[42:43], 0, v[8:9]
	v_lshl_add_u64 v[16:17], v[46:47], 0, v[14:15]
	v_lshl_add_u64 v[18:19], v[44:45], 0, v[14:15]
	global_load_dword v115, v[4:5], off
	global_load_dword v116, v[6:7], off
	global_load_dword v118, v[2:3], off
	global_load_dword v119, v[10:11], off
	global_load_dword v121, v[12:13], off
	global_load_dword v122, v[8:9], off
	global_load_dword v124, v[16:17], off
	global_load_dword v127, v[18:19], off
	v_add_u32_e32 v4, s76, v112
	v_add_u32_e32 v114, s10, v113
	v_ashrrev_i32_e32 v5, 31, v4
	v_add_u32_e32 v10, s76, v113
	v_add_u32_e32 v16, s76, v114
	v_lshlrev_b64 v[4:5], 13, v[4:5]
	v_ashrrev_i32_e32 v11, 31, v10
	v_ashrrev_i32_e32 v17, 31, v16
	v_lshl_add_u64 v[2:3], v[42:43], 0, v[14:15]
	v_lshl_add_u64 v[6:7], v[46:47], 0, v[4:5]
	v_lshlrev_b64 v[10:11], 13, v[10:11]
	v_lshlrev_b64 v[16:17], 13, v[16:17]
	v_add_u32_e32 v117, s10, v114
	v_lshl_add_u64 v[8:9], v[44:45], 0, v[4:5]
	v_lshl_add_u64 v[4:5], v[42:43], 0, v[4:5]
	v_lshl_add_u64 v[12:13], v[46:47], 0, v[10:11]
	v_lshl_add_u64 v[14:15], v[44:45], 0, v[10:11]
	v_lshl_add_u64 v[10:11], v[42:43], 0, v[10:11]
	v_lshl_add_u64 v[18:19], v[46:47], 0, v[16:17]
	global_load_dword v130, v[2:3], off
	global_load_dword v132, v[6:7], off
	global_load_dword v133, v[8:9], off
	global_load_dword v135, v[4:5], off
	global_load_dword v136, v[12:13], off
	global_load_dword v137, v[14:15], off
	global_load_dword v138, v[10:11], off
	global_load_dword v143, v[18:19], off
	v_add_u32_e32 v6, s76, v117
	v_add_u32_e32 v120, s10, v117
	v_ashrrev_i32_e32 v7, 31, v6
	v_add_u32_e32 v12, s76, v120
	v_lshlrev_b64 v[6:7], 13, v[6:7]
	v_ashrrev_i32_e32 v13, 31, v12
	v_add_u32_e32 v123, s10, v120
	v_lshl_add_u64 v[2:3], v[44:45], 0, v[16:17]
	v_lshl_add_u64 v[8:9], v[46:47], 0, v[6:7]
	v_lshlrev_b64 v[12:13], 13, v[12:13]
	v_add_u32_e32 v125, s10, v123
	v_lshl_add_u64 v[4:5], v[42:43], 0, v[16:17]
	v_lshl_add_u64 v[10:11], v[44:45], 0, v[6:7]
	v_lshl_add_u64 v[6:7], v[42:43], 0, v[6:7]
	v_lshl_add_u64 v[14:15], v[46:47], 0, v[12:13]
	v_lshl_add_u64 v[16:17], v[44:45], 0, v[12:13]
	v_lshl_add_u64 v[12:13], v[42:43], 0, v[12:13]
	global_load_dword v144, v[2:3], off
	global_load_dword v145, v[4:5], off
	global_load_dword v146, v[8:9], off
	global_load_dword v147, v[10:11], off
	global_load_dword v148, v[6:7], off
	global_load_dword v149, v[14:15], off
	global_load_dword v150, v[16:17], off
	global_load_dword v151, v[12:13], off
	v_add_u32_e32 v2, s76, v123
	v_add_u32_e32 v8, s76, v125
	v_add_u32_e32 v126, s10, v125
	v_ashrrev_i32_e32 v3, 31, v2
	v_ashrrev_i32_e32 v9, 31, v8
	v_add_u32_e32 v14, s76, v126
	v_lshlrev_b64 v[2:3], 13, v[2:3]
	v_lshlrev_b64 v[8:9], 13, v[8:9]
	v_ashrrev_i32_e32 v15, 31, v14
	v_add_u32_e32 v128, s10, v126
	v_lshl_add_u64 v[4:5], v[46:47], 0, v[2:3]
	v_lshl_add_u64 v[10:11], v[46:47], 0, v[8:9]
	v_lshlrev_b64 v[14:15], 13, v[14:15]
	v_add_u32_e32 v129, s10, v128
	v_lshl_add_u64 v[6:7], v[44:45], 0, v[2:3]
	v_lshl_add_u64 v[2:3], v[42:43], 0, v[2:3]
	v_lshl_add_u64 v[12:13], v[44:45], 0, v[8:9]
	v_lshl_add_u64 v[8:9], v[42:43], 0, v[8:9]
	v_lshl_add_u64 v[16:17], v[46:47], 0, v[14:15]
	v_lshl_add_u64 v[18:19], v[44:45], 0, v[14:15]
	global_load_dword v152, v[4:5], off
	global_load_dword v153, v[6:7], off
	global_load_dword v154, v[2:3], off
	global_load_dword v155, v[10:11], off
	global_load_dword v156, v[12:13], off
	global_load_dword v157, v[8:9], off
	global_load_dword v158, v[16:17], off
	global_load_dword v159, v[18:19], off
	v_add_u32_e32 v4, s76, v128
	v_add_u32_e32 v10, s76, v129
	v_add_u32_e32 v131, s10, v129
	v_ashrrev_i32_e32 v5, 31, v4
	v_ashrrev_i32_e32 v11, 31, v10
	v_add_u32_e32 v16, s76, v131
	v_lshlrev_b64 v[4:5], 13, v[4:5]
	v_lshlrev_b64 v[10:11], 13, v[10:11]
	v_ashrrev_i32_e32 v17, 31, v16
	v_lshl_add_u64 v[2:3], v[42:43], 0, v[14:15]
	v_lshl_add_u64 v[6:7], v[46:47], 0, v[4:5]
	v_lshl_add_u64 v[12:13], v[46:47], 0, v[10:11]
	v_lshlrev_b64 v[16:17], 13, v[16:17]
	v_add_u32_e32 v134, s10, v131
	v_lshl_add_u64 v[8:9], v[44:45], 0, v[4:5]
	v_lshl_add_u64 v[4:5], v[42:43], 0, v[4:5]
	v_lshl_add_u64 v[14:15], v[44:45], 0, v[10:11]
	v_lshl_add_u64 v[10:11], v[42:43], 0, v[10:11]
	v_lshl_add_u64 v[18:19], v[46:47], 0, v[16:17]
	global_load_dword v160, v[2:3], off
	global_load_dword v161, v[6:7], off
	global_load_dword v162, v[8:9], off
	global_load_dword v163, v[4:5], off
	global_load_dword v164, v[12:13], off
	global_load_dword v165, v[14:15], off
	global_load_dword v166, v[10:11], off
	global_load_dword v167, v[18:19], off
	v_add_u32_e32 v6, s76, v134
	v_mad_i32_i24 v12, s10, v63, v20
	v_ashrrev_i32_e32 v7, 31, v6
	v_ashrrev_i32_e32 v13, 31, v12
	v_lshl_add_u64 v[2:3], v[44:45], 0, v[16:17]
	v_lshlrev_b64 v[6:7], 13, v[6:7]
	v_lshlrev_b64 v[12:13], 13, v[12:13]
	v_lshl_add_u64 v[4:5], v[42:43], 0, v[16:17]
	v_lshl_add_u64 v[8:9], v[46:47], 0, v[6:7]
	v_lshl_add_u64 v[10:11], v[44:45], 0, v[6:7]
	v_lshl_add_u64 v[6:7], v[42:43], 0, v[6:7]
	v_lshl_add_u64 v[14:15], v[46:47], 0, v[12:13]
	v_lshl_add_u64 v[16:17], v[44:45], 0, v[12:13]
	v_lshl_add_u64 v[12:13], v[42:43], 0, v[12:13]
	global_load_dword v168, v[2:3], off
	global_load_dword v169, v[4:5], off
	global_load_dword v170, v[8:9], off
	global_load_dword v171, v[10:11], off
	global_load_dword v172, v[6:7], off
	global_load_dword v173, v[14:15], off
	global_load_dword v174, v[16:17], off
	global_load_dword v175, v[12:13], off
	v_mad_i32_i24 v2, s10, v33, v20
	v_ashrrev_i32_e32 v3, 31, v2
	v_lshl_add_u64 v[48:49], v[38:39], 1, s[72:73]
	v_lshlrev_b64 v[2:3], 13, v[2:3]
	v_lshl_add_u64 v[2:3], v[48:49], 0, v[2:3]
	global_load_dwordx4 v[18:21], v[2:3], off
	s_lshl_b32 s65, s65, 13
	s_add_u32 s31, s74, s75
	s_addc_u32 s11, s11, 0
	s_add_u32 s31, s31, s77
	s_addc_u32 s11, s11, 0
	s_add_u32 s62, s31, s52
	s_addc_u32 s63, s11, 0
	v_mov_b32_e32 v41, v0
	v_mov_b32_e32 v2, 0
	s_mov_b32 s57, 0
	v_mul_i32_i24_e32 v139, s10, v52
	v_mul_i32_i24_e32 v140, s10, v63
	v_mul_i32_i24_e32 v141, s10, v33
	v_lshl_add_u64 v[50:51], s[62:63], 0, v[40:41]
	v_mul_lo_u32 v41, s10, v91
	v_mul_lo_u32 v142, s10, v96
	s_movk_i32 s74, 0xff40
	s_movk_i32 s75, 0x20bf
	v_mov_b32_e32 v3, v2
	v_mov_b32_e32 v4, v2
	v_mov_b32_e32 v5, v2
	v_mov_b32_e32 v14, v2
	v_mov_b32_e32 v15, v2
	v_mov_b32_e32 v16, v2
	v_mov_b32_e32 v17, v2
	v_mov_b32_e32 v6, v2
	v_mov_b32_e32 v7, v2
	v_mov_b32_e32 v8, v2
	v_mov_b32_e32 v9, v2
	v_mov_b32_e32 v10, v2
	v_mov_b32_e32 v11, v2
	v_mov_b32_e32 v12, v2
	v_mov_b32_e32 v13, v2
	v_readfirstlane_b32 s82, v42
	v_readfirstlane_b32 s83, v43
	s_cmp_lg_u32 s70, 0
	s_cselect_b32 s91, 0, 0xffffffd0
	s_cselect_b32 s32, 0, 0xffffffc1
	s_cselect_b32 s99, 0, -1
	s_mov_b32 s98, 0x2000
	s_cselect_b32 s98, s98, 0xffffe000
	v_subrev_u32_e32 v114, s91, v139
	v_subrev_u32_e32 v113, s32, v141
	v_lshlrev_b32_e32 v114, 13, v114
	v_lshlrev_b32_e32 v113, 13, v113
	v_subrev_u32_e32 v110, s82, v46
	v_subrev_u32_e32 v111, s82, v44
	v_subrev_u32_e32 v112, s82, v42
	v_add_u32_e32 v113, v113, v48
	v_add_u32_e32 v110, v110, v114
	v_add_u32_e32 v111, v111, v114
	v_add_u32_e32 v112, v112, v114
	v_subrev_u32_e32 v113, s82, v113
	s_branch .LBB0_1317

.LBB0_1317:
	s_waitcnt vmcnt(48)
	v_perm_b32 v26, v115, v115, v32
	v_add_f32_e32 v176, 0, v26
	s_waitcnt vmcnt(45)
	v_perm_b32 v26, v119, v119, v32
	v_add_f32_e32 v177, v176, v26
	s_waitcnt vmcnt(42)
	v_perm_b32 v26, v124, v124, v32
	v_add_f32_e32 v178, v177, v26
	s_waitcnt vmcnt(39)
	v_perm_b32 v26, v132, v132, v32
	v_add_f32_e32 v179, v178, v26
	s_waitcnt vmcnt(36)
	v_perm_b32 v26, v136, v136, v32
	v_add_f32_e32 v180, v179, v26
	s_waitcnt vmcnt(33)
	v_perm_b32 v26, v143, v143, v32
	v_add_f32_e32 v181, v180, v26
	s_waitcnt vmcnt(30)
	v_perm_b32 v26, v146, v146, v32
	v_add_f32_e32 v182, v181, v26
	s_waitcnt vmcnt(27)
	v_perm_b32 v26, v149, v149, v32
	v_add_f32_e32 v183, v182, v26
	s_waitcnt vmcnt(24)
	v_perm_b32 v26, v152, v152, v32
	v_add_f32_e32 v184, v183, v26
	s_waitcnt vmcnt(21)
	v_perm_b32 v26, v155, v155, v32
	v_add_f32_e32 v185, v184, v26
	s_waitcnt vmcnt(18)
	v_perm_b32 v26, v158, v158, v32
	v_add_f32_e32 v186, v185, v26
	s_waitcnt vmcnt(15)
	v_perm_b32 v26, v161, v161, v32
	v_add_f32_e32 v187, v186, v26
	s_waitcnt vmcnt(12)
	v_perm_b32 v26, v164, v164, v32
	v_add_f32_e32 v188, v187, v26
	s_waitcnt vmcnt(9)
	v_perm_b32 v26, v167, v167, v32
	v_add_f32_e32 v189, v188, v26
	s_waitcnt vmcnt(6)
	v_perm_b32 v26, v170, v170, v32
	v_add_f32_e32 v190, v189, v26
	s_waitcnt vmcnt(3)
	v_perm_b32 v26, v173, v173, v32
	v_add_f32_e32 v191, v190, v26
	ds_bpermute_b32 v26, v53, v191
	ds_bpermute_b32 v28, v54, v191
	ds_bpermute_b32 v27, v55, v191
	ds_bpermute_b32 v29, v56, v191
	v_cvt_pk_bf16_f32 v22, v2, v3
	v_cvt_pk_bf16_f32 v23, v4, v5
	v_cvt_pk_bf16_f32 v24, v14, v15
	v_cvt_pk_bf16_f32 v25, v16, v17
	s_add_i32 s78, s74, 0x100
	s_add_i32 s32, s75, 0xffffe000
	s_cmp_lg_u32 s70, 0
	s_cselect_b32 s78, s78, s32
	s_cselect_b32 s32, s74, s75
	s_add_i32 s32, s32, s65
	s_add_i32 s78, s78, s56
	s_cmp_gt_u32 s57, 2
	s_cselect_b32 s32, s32, s78
	s_cmp_eq_u32 s75, -1
	s_cselect_b32 s32, s76, s32
	s_add_i32 s32, s32, s91
	s_lshl_b32 s32, s32, 13
	s_add_u32 s80, s82, s32
	s_addc_u32 s81, s83, 0
	s_waitcnt lgkmcnt(0)
	s_barrier
	ds_write2_b64 v103, v[22:23], v[24:25] offset1:4
	v_cvt_pk_bf16_f32 v22, v6, v7
	v_cvt_pk_bf16_f32 v23, v8, v9
	v_cvt_pk_bf16_f32 v24, v10, v11
	v_cvt_pk_bf16_f32 v25, v12, v13
	ds_write2_b64 v103, v[22:23], v[24:25] offset0:8 offset1:12
	v_cndmask_b32_e64 v22, v26, 0, s[0:1]
	v_cndmask_b32_e64 v23, 0, v28, s[2:3]
	v_add_f32_e32 v22, v22, v23
	v_cndmask_b32_e64 v23, 0, v27, s[4:5]
	v_add_f32_e32 v192, v22, v23
	v_pk_add_f32 v[22:23], v[26:27], v[28:29]
	v_add_f32_e32 v22, v22, v23
	v_add_f32_e32 v23, v176, v192
	v_exp_f32_e32 v25, v23
	v_perm_b32 v24, v116, v116, v32
	v_exp_f32_e64 v26, -v23
	v_exp_f32_e32 v22, v22
	v_mul_f32_e32 v23, v25, v24
	v_cvt_pk_bf16_f32 v23, v23, s0
	ds_write_b16 v64, v23
	v_add_f32_e32 v23, v177, v192
	v_exp_f32_e32 v24, v23
	v_exp_f32_e64 v27, -v23
	v_perm_b32 v25, v121, v121, v32
	v_perm_b32 v29, v122, v122, v1
	v_perm_b32 v28, v118, v118, v32
	global_load_dword v115, v110, s[80:81]
	global_load_dword v116, v111, s[80:81]
	global_load_dword v118, v112, s[80:81]
	s_add_u32 s80, s80, s98
	s_addc_u32 s81, s81, s99
	global_load_dword v119, v110, s[80:81]
	global_load_dword v121, v111, s[80:81]
	global_load_dword v122, v112, s[80:81]
	s_add_u32 s80, s80, s98
	s_addc_u32 s81, s81, s99
	v_mul_f32_e32 v23, v24, v25
	v_mul_f32_e32 v24, v26, v28
	v_cvt_pk_bf16_f32 v23, v23, s0
	v_cvt_pk_bf16_f32 v24, v24, s0
	ds_write_b16 v64, v24 offset:17408
	v_pk_mul_f32 v[24:25], v[22:23], v[26:27] op_sel_hi:[0,1]
	ds_write_b16 v65, v23
	v_mul_f32_e32 v23, v27, v29
	v_cvt_pk_bf16_f32 v23, v23, s0
	ds_write_b16 v65, v23 offset:17408
	v_add_f32_e32 v23, v178, v192
	v_pk_mul_f32 v[24:25], v[24:25], v[28:29]
	v_exp_f32_e32 v28, v23
	v_perm_b32 v27, v127, v127, v32
	v_exp_f32_e64 v26, -v23
	v_mul_f32_e32 v23, v28, v27
	v_cvt_pk_bf16_f32 v23, v23, s0
	ds_write_b16 v66, v23
	v_add_f32_e32 v23, v179, v192
	v_exp_f32_e32 v28, v23
	v_perm_b32 v177, v133, v133, v32
	v_exp_f32_e64 v27, -v23
	v_mul_f32_e32 v23, v28, v177
	v_perm_b32 v28, v130, v130, v32
	global_load_dword v124, v110, s[80:81]
	global_load_dword v127, v111, s[80:81]
	global_load_dword v130, v112, s[80:81]
	s_add_u32 s80, s80, s98
	s_addc_u32 s81, s81, s99
	v_mul_f32_e32 v176, v26, v28
	v_cvt_pk_bf16_f32 v23, v23, s0
	v_perm_b32 v29, v135, v135, v1
	global_load_dword v132, v110, s[80:81]
	global_load_dword v133, v111, s[80:81]
	global_load_dword v135, v112, s[80:81]
	s_add_u32 s80, s80, s98
	s_addc_u32 s81, s81, s99
	v_cvt_pk_bf16_f32 v176, v176, s0
	ds_write_b16 v66, v176 offset:17408
	v_pk_mul_f32 v[176:177], v[22:23], v[26:27] op_sel_hi:[0,1]
	ds_write_b16 v67, v23
	v_mul_f32_e32 v23, v27, v29
	v_cvt_pk_bf16_f32 v23, v23, s0
	ds_write_b16 v67, v23 offset:17408
	v_add_f32_e32 v23, v180, v192
	v_pk_mul_f32 v[176:177], v[176:177], v[28:29]
	v_exp_f32_e32 v28, v23
	v_perm_b32 v27, v137, v137, v32
	v_exp_f32_e64 v26, -v23
	v_mul_f32_e32 v23, v28, v27
	v_cvt_pk_bf16_f32 v23, v23, s0
	ds_write_b16 v68, v23
	v_add_f32_e32 v23, v181, v192
	v_exp_f32_e32 v28, v23
	v_perm_b32 v179, v144, v144, v32
	v_exp_f32_e64 v27, -v23
	v_mul_f32_e32 v23, v28, v179
	v_perm_b32 v28, v138, v138, v32
	global_load_dword v136, v110, s[80:81]
	global_load_dword v137, v111, s[80:81]
	global_load_dword v138, v112, s[80:81]
	s_add_u32 s80, s80, s98
	s_addc_u32 s81, s81, s99
	v_mul_f32_e32 v178, v26, v28
	v_cvt_pk_bf16_f32 v23, v23, s0
	v_perm_b32 v29, v145, v145, v1
	global_load_dword v143, v110, s[80:81]
	global_load_dword v144, v111, s[80:81]
	global_load_dword v145, v112, s[80:81]
	s_add_u32 s80, s80, s98
	s_addc_u32 s81, s81, s99
	v_cvt_pk_bf16_f32 v178, v178, s0
	ds_write_b16 v68, v178 offset:17408
	v_pk_mul_f32 v[178:179], v[22:23], v[26:27] op_sel_hi:[0,1]
	ds_write_b16 v69, v23
	v_mul_f32_e32 v23, v27, v29
	v_cvt_pk_bf16_f32 v23, v23, s0
	ds_write_b16 v69, v23 offset:17408
	v_add_f32_e32 v23, v182, v192
	v_pk_mul_f32 v[178:179], v[178:179], v[28:29]
	v_exp_f32_e32 v28, v23
	v_perm_b32 v27, v147, v147, v32
	v_exp_f32_e64 v26, -v23
	v_mul_f32_e32 v23, v28, v27
	v_cvt_pk_bf16_f32 v23, v23, s0
	ds_write_b16 v70, v23
	v_add_f32_e32 v23, v183, v192
	v_exp_f32_e32 v28, v23
	v_perm_b32 v181, v150, v150, v32
	v_exp_f32_e64 v27, -v23
	v_mul_f32_e32 v23, v28, v181
	v_perm_b32 v28, v148, v148, v32
	global_load_dword v146, v110, s[80:81]
	global_load_dword v147, v111, s[80:81]
	global_load_dword v148, v112, s[80:81]
	s_add_u32 s80, s80, s98
	s_addc_u32 s81, s81, s99
	v_mul_f32_e32 v180, v26, v28
	v_cvt_pk_bf16_f32 v23, v23, s0
	v_perm_b32 v29, v151, v151, v1
	global_load_dword v149, v110, s[80:81]
	global_load_dword v150, v111, s[80:81]
	global_load_dword v151, v112, s[80:81]
	s_add_u32 s80, s80, s98
	s_addc_u32 s81, s81, s99
	v_cvt_pk_bf16_f32 v180, v180, s0
	ds_write_b16 v70, v180 offset:17408
	v_pk_mul_f32 v[180:181], v[22:23], v[26:27] op_sel_hi:[0,1]
	ds_write_b16 v71, v23
	v_mul_f32_e32 v23, v27, v29
	v_cvt_pk_bf16_f32 v23, v23, s0
	ds_write_b16 v71, v23 offset:17408
	v_add_f32_e32 v23, v184, v192
	v_pk_mul_f32 v[180:181], v[180:181], v[28:29]
	v_exp_f32_e32 v28, v23
	v_perm_b32 v27, v153, v153, v32
	v_exp_f32_e64 v26, -v23
	v_mul_f32_e32 v23, v28, v27
	v_cvt_pk_bf16_f32 v23, v23, s0
	ds_write_b16 v72, v23
	v_add_f32_e32 v23, v185, v192
	v_exp_f32_e32 v28, v23
	v_perm_b32 v183, v156, v156, v32
	v_exp_f32_e64 v27, -v23
	v_mul_f32_e32 v23, v28, v183
	v_perm_b32 v28, v154, v154, v32
	global_load_dword v152, v110, s[80:81]
	global_load_dword v153, v111, s[80:81]
	global_load_dword v154, v112, s[80:81]
	s_add_u32 s80, s80, s98
	s_addc_u32 s81, s81, s99
	v_mul_f32_e32 v182, v26, v28
	v_cvt_pk_bf16_f32 v23, v23, s0
	v_perm_b32 v29, v157, v157, v1
	global_load_dword v155, v110, s[80:81]
	global_load_dword v156, v111, s[80:81]
	global_load_dword v157, v112, s[80:81]
	s_add_u32 s80, s80, s98
	s_addc_u32 s81, s81, s99
	v_cvt_pk_bf16_f32 v182, v182, s0
	ds_write_b16 v72, v182 offset:17408
	v_pk_mul_f32 v[182:183], v[22:23], v[26:27] op_sel_hi:[0,1]
	ds_write_b16 v73, v23
	v_mul_f32_e32 v23, v27, v29
	v_cvt_pk_bf16_f32 v23, v23, s0
	ds_write_b16 v73, v23 offset:17408
	v_add_f32_e32 v23, v186, v192
	v_pk_mul_f32 v[182:183], v[182:183], v[28:29]
	v_exp_f32_e32 v28, v23
	v_perm_b32 v27, v159, v159, v32
	v_exp_f32_e64 v26, -v23
	v_mul_f32_e32 v23, v28, v27
	v_cvt_pk_bf16_f32 v23, v23, s0
	ds_write_b16 v74, v23
	v_add_f32_e32 v23, v187, v192
	v_exp_f32_e32 v28, v23
	v_perm_b32 v185, v162, v162, v32
	v_exp_f32_e64 v27, -v23
	v_mul_f32_e32 v23, v28, v185
	v_perm_b32 v28, v160, v160, v32
	global_load_dword v158, v110, s[80:81]
	global_load_dword v159, v111, s[80:81]
	global_load_dword v160, v112, s[80:81]
	s_add_u32 s80, s80, s98
	s_addc_u32 s81, s81, s99
	v_mul_f32_e32 v184, v26, v28
	v_cvt_pk_bf16_f32 v23, v23, s0
	v_perm_b32 v29, v163, v163, v1
	global_load_dword v161, v110, s[80:81]
	global_load_dword v162, v111, s[80:81]
	global_load_dword v163, v112, s[80:81]
	s_add_u32 s80, s80, s98
	s_addc_u32 s81, s81, s99
	v_cvt_pk_bf16_f32 v184, v184, s0
	ds_write_b16 v74, v184 offset:17408
	v_pk_mul_f32 v[184:185], v[22:23], v[26:27] op_sel_hi:[0,1]
	ds_write_b16 v75, v23
	v_mul_f32_e32 v23, v27, v29
	v_cvt_pk_bf16_f32 v23, v23, s0
	ds_write_b16 v75, v23 offset:17408
	v_add_f32_e32 v23, v188, v192
	v_pk_mul_f32 v[184:185], v[184:185], v[28:29]
	v_exp_f32_e32 v28, v23
	v_perm_b32 v27, v165, v165, v32
	v_exp_f32_e64 v26, -v23
	v_mul_f32_e32 v23, v28, v27
	v_cvt_pk_bf16_f32 v23, v23, s0
	ds_write_b16 v76, v23
	v_add_f32_e32 v23, v189, v192
	v_exp_f32_e32 v28, v23
	v_perm_b32 v187, v168, v168, v32
	v_exp_f32_e64 v27, -v23
	v_mul_f32_e32 v23, v28, v187
	v_perm_b32 v28, v166, v166, v32
	global_load_dword v164, v110, s[80:81]
	global_load_dword v165, v111, s[80:81]
	global_load_dword v166, v112, s[80:81]
	s_add_u32 s80, s80, s98
	s_addc_u32 s81, s81, s99
	v_mul_f32_e32 v186, v26, v28
	v_cvt_pk_bf16_f32 v23, v23, s0
	v_perm_b32 v29, v169, v169, v1
	global_load_dword v167, v110, s[80:81]
	global_load_dword v168, v111, s[80:81]
	global_load_dword v169, v112, s[80:81]
	s_add_u32 s80, s80, s98
	s_addc_u32 s81, s81, s99
	v_cvt_pk_bf16_f32 v186, v186, s0
	ds_write_b16 v76, v186 offset:17408
	v_pk_mul_f32 v[186:187], v[22:23], v[26:27] op_sel_hi:[0,1]
	ds_write_b16 v77, v23
	v_mul_f32_e32 v23, v27, v29
	v_cvt_pk_bf16_f32 v23, v23, s0
	ds_write_b16 v77, v23 offset:17408
	v_add_f32_e32 v23, v190, v192
	v_exp_f32_e32 v27, v23
	v_perm_b32 v26, v171, v171, v32
	v_pk_mul_f32 v[186:187], v[186:187], v[28:29]
	v_exp_f32_e64 v28, -v23
	v_mul_f32_e32 v23, v27, v26
	v_cvt_pk_bf16_f32 v23, v23, s0
	ds_write_b16 v78, v23
	v_add_f32_e32 v23, v191, v192
	v_exp_f32_e32 v26, v23
	s_waitcnt vmcnt(43)
	v_exp_f32_e64 v29, -v23
	v_perm_b32 v27, v174, v174, v32
	v_perm_b32 v189, v175, v175, v1
	v_perm_b32 v188, v172, v172, v32
	global_load_dword v170, v110, s[80:81]
	global_load_dword v171, v111, s[80:81]
	global_load_dword v172, v112, s[80:81]
	s_add_u32 s80, s80, s98
	s_addc_u32 s81, s81, s99
	global_load_dword v173, v110, s[80:81]
	global_load_dword v174, v111, s[80:81]
	global_load_dword v175, v112, s[80:81]
	v_mul_f32_e32 v23, v26, v27
	v_mul_f32_e32 v26, v28, v188
	v_cvt_pk_bf16_f32 v23, v23, s0
	v_cvt_pk_bf16_f32 v26, v26, s0
	ds_write_b16 v78, v26 offset:17408
	ds_write_b16 v79, v23
	v_mul_f32_e32 v23, v29, v189
	v_cvt_pk_bf16_f32 v23, v23, s0
	v_pk_mul_f32 v[28:29], v[22:23], v[28:29] op_sel_hi:[0,1]
	v_cvt_pk_bf16_f32 v24, v24, v25
	v_cvt_pk_bf16_f32 v25, v176, v177
	v_cvt_pk_bf16_f32 v26, v178, v179
	v_cvt_pk_bf16_f32 v27, v180, v181
	v_pk_mul_f32 v[28:29], v[28:29], v[188:189]
	ds_write_b16 v79, v23 offset:17408
	v_cvt_pk_bf16_f32 v176, v182, v183
	v_cvt_pk_bf16_f32 v177, v184, v185
	v_cvt_pk_bf16_f32 v178, v186, v187
	v_cvt_pk_bf16_f32 v179, v28, v29
	ds_write_b128 v57, v[24:27] offset:34816
	ds_write_b128 v57, v[176:179] offset:34832
	s_and_saveexec_b64 s[72:73], s[0:1]
	ds_write_b32 v61, v22
	s_or_b64 exec, exec, s[72:73]
	s_cmp_eq_u32 s75, -1
	s_mov_b32 s10, s76
	s_waitcnt vmcnt(48)
	ds_write_b16 v58, v18 offset:53248
	ds_write_b16_d16_hi v58, v18 offset:53392
	ds_write_b16 v58, v19 offset:53536
	ds_write_b16_d16_hi v58, v19 offset:53680
	ds_write_b16 v58, v20 offset:53824
	ds_write_b16_d16_hi v58, v20 offset:53968
	ds_write_b16 v58, v21 offset:54112
	ds_write_b16_d16_hi v59, v21 offset:53248
	s_cbranch_scc1 .LBB0_1325
	s_cmp_gt_u32 s57, 2
	s_mov_b64 s[72:73], -1
	s_cbranch_scc0 .LBB0_1322
	s_and_b64 s[10:11], s[70:71], exec
	s_cselect_b32 s10, s74, s75
	s_add_i32 s10, s10, s65
	s_mov_b64 s[72:73], 0

.LBB0_1324:
	s_and_b64 s[72:73], s[70:71], exec
	s_cselect_b32 s72, 0xfffe2000, 0
	s_cselect_b32 s73, -1, 0
	s_add_u32 s80, s80, s72
	s_addc_u32 s81, s81, s73
	global_load_dwordx4 v[18:21], v113, s[80:81]
